# grid barrier: each workgroup issues its acquire invalidate at arrival (leader together with the write-back) instead of after the release
# speedup vs baseline: 1.0052x; 1.0038x over previous
; __device__ __forceinline__ unsigned xb_ld(unsigned* p)              { return __hip_atomic_load(p, __ATOMIC_RELAXED, __HIP_MEMORY_SCOPE_AGENT); }
; __device__ __forceinline__ unsigned xb_add(unsigned* p, unsigned v) { return __hip_atomic_fetch_add(p, v, __ATOMIC_RELAXED, __HIP_MEMORY_SCOPE_AGENT); }
; #define XB_SPIN(cond, bar) do { unsigned _sp = 0; while (cond) { __builtin_amdgcn_s_sleep(1); \
;     if ((++_sp & 255u) == 0u) { if (xb_ld(&(bar)[XB_TMO])) break; if (_sp > XB_SPIN_CAP) { atomicAdd(&(bar)[XB_TMO], 1u); break; } } } } while (0)
; __device__ __forceinline__ void xcd_barrier(unsigned* bar, volatile LAS unsigned* st, bool tid0) {
;     ...
;         const unsigned old = xb_add(&bar[XB_XSUB(x)], 1u);
;         const unsigned gen = old / nloc;
;         if (old + 1u == (gen + 1u) * nloc) {
;             __builtin_amdgcn_fence(__ATOMIC_RELEASE, "agent");
;             asm volatile("s_waitcnt vmcnt(0)" ::: "memory");
;             const unsigned og = xb_add(&bar[XB_TOP], 1u);
;             const unsigned tg = og / nx;
;             if (og + 1u == (tg + 1u) * nx) xb_add(&bar[XB_TOPGEN], 1u);
;             else XB_SPIN(xb_ld(&bar[XB_TOPGEN]) == tg, bar);
;             __builtin_amdgcn_fence(__ATOMIC_ACQUIRE, "agent");
;             xb_add(&bar[XB_XGEN(x)], 1u);
;             asm volatile("s_waitcnt vmcnt(0)" ::: "memory");
;         } else {
;             XB_SPIN(xb_ld(&bar[XB_XGEN(x)]) == gen, bar);
;             __builtin_amdgcn_fence(__ATOMIC_ACQUIRE, "agent");
;             asm volatile("s_waitcnt vmcnt(0)" ::: "memory");
.LBB0_47:
	s_or_b64 exec, exec, s[8:9]
	v_cvt_f32_u32_e32 v5, v3
	s_waitcnt vmcnt(0)
	v_readfirstlane_b32 s2, v4
	v_sub_u32_e32 v4, 0, v3
	v_rcp_iflag_f32_e32 v5, v5
	v_add_u32_e32 v6, s2, v2
	v_mul_f32_e32 v5, 0x4f7ffffe, v5
	v_cvt_u32_f32_e32 v5, v5
	v_mul_lo_u32 v2, v4, v5
	v_mul_hi_u32 v2, v5, v2
	v_add_u32_e32 v2, v5, v2
	v_mul_hi_u32 v2, v6, v2
	v_mul_lo_u32 v4, v2, v3
	v_sub_u32_e32 v4, v6, v4
	v_add_u32_e32 v5, 1, v2
	v_cmp_ge_u32_e32 vcc, v4, v3
	s_nop 1
	v_cndmask_b32_e32 v2, v2, v5, vcc
	v_sub_u32_e32 v5, v4, v3
	v_cndmask_b32_e32 v4, v4, v5, vcc
	v_add_u32_e32 v5, 1, v2
	v_cmp_ge_u32_e32 vcc, v4, v3
	v_add_u32_e32 v4, 1, v6
	s_nop 0
	v_cndmask_b32_e32 v2, v2, v5, vcc
	v_mul_lo_u32 v5, v3, v2
	v_add_u32_e32 v3, v5, v3
	v_cmp_ne_u32_e32 vcc, v4, v3
	s_and_saveexec_b64 s[2:3], vcc
	s_xor_b64 s[6:7], exec, s[2:3]
	s_cbranch_execz .LBB0_61
	s_waitcnt lgkmcnt(0)
	v_mov_b32_e32 v1, 0x2000
	buffer_inv sc1
	global_load_dword v1, v1, s[4:5] offset:1024 sc1
	s_add_u32 s10, s4, 0x2400
	s_addc_u32 s11, s5, 0
	s_waitcnt vmcnt(0)
	v_cmp_eq_u32_e32 vcc, v1, v2
	s_and_saveexec_b64 s[8:9], vcc
	s_cbranch_execz .LBB0_60
	s_mov_b32 s2, 1
	s_mov_b64 s[12:13], 0
	v_mov_b32_e32 v1, 0
	s_branch .LBB0_51

; __device__ __forceinline__ unsigned xb_ld(unsigned* p)              { return __hip_atomic_load(p, __ATOMIC_RELAXED, __HIP_MEMORY_SCOPE_AGENT); }
; __device__ __forceinline__ unsigned xb_add(unsigned* p, unsigned v) { return __hip_atomic_fetch_add(p, v, __ATOMIC_RELAXED, __HIP_MEMORY_SCOPE_AGENT); }
; #define XB_SPIN(cond, bar) do { unsigned _sp = 0; while (cond) { __builtin_amdgcn_s_sleep(1); \
;     if ((++_sp & 255u) == 0u) { if (xb_ld(&(bar)[XB_TMO])) break; if (_sp > XB_SPIN_CAP) { atomicAdd(&(bar)[XB_TMO], 1u); break; } } } } while (0)
; __device__ __forceinline__ void xcd_barrier(unsigned* bar, volatile LAS unsigned* st, bool tid0) {
;     ...
;         if (old + 1u == (gen + 1u) * nloc) {
;             __builtin_amdgcn_fence(__ATOMIC_RELEASE, "agent");
;             asm volatile("s_waitcnt vmcnt(0)" ::: "memory");
;             const unsigned og = xb_add(&bar[XB_TOP], 1u);
;             const unsigned tg = og / nx;
;             if (og + 1u == (tg + 1u) * nx) xb_add(&bar[XB_TOPGEN], 1u);
;             else XB_SPIN(xb_ld(&bar[XB_TOPGEN]) == tg, bar);
;             __builtin_amdgcn_fence(__ATOMIC_ACQUIRE, "agent");
;             xb_add(&bar[XB_XGEN(x)], 1u);
;             asm volatile("s_waitcnt vmcnt(0)" ::: "memory");
;         } else {
;             XB_SPIN(xb_ld(&bar[XB_XGEN(x)]) == gen, bar);
;             __builtin_amdgcn_fence(__ATOMIC_ACQUIRE, "agent");
;             asm volatile("s_waitcnt vmcnt(0)" ::: "memory");
.LBB0_60:
	s_or_b64 exec, exec, s[8:9]
	s_waitcnt vmcnt(0)
	s_waitcnt vmcnt(0)
.LBB0_61:
	s_andn2_saveexec_b64 s[2:3], s[6:7]
	s_cbranch_execz .LBB0_81
	s_mov_b64 s[6:7], exec
	buffer_wbl2 sc1
	buffer_inv sc1
	s_waitcnt lgkmcnt(0)
	s_waitcnt vmcnt(0)
	v_mbcnt_lo_u32_b32 v2, s6, 0
	v_mbcnt_hi_u32_b32 v2, s7, v2
	v_cmp_eq_u32_e32 vcc, 0, v2
	s_and_saveexec_b64 s[8:9], vcc
	s_cbranch_execz .LBB0_64
	s_bcnt1_i32_b64 s2, s[6:7]
	v_mov_b32_e32 v3, 0x3000
	v_mov_b32_e32 v4, s2
	global_atomic_add v3, v3, v4, s[52:53] offset:1024 sc0

; __device__ __forceinline__ unsigned xb_ld(unsigned* p)              { return __hip_atomic_load(p, __ATOMIC_RELAXED, __HIP_MEMORY_SCOPE_AGENT); }
; __device__ __forceinline__ unsigned xb_add(unsigned* p, unsigned v) { return __hip_atomic_fetch_add(p, v, __ATOMIC_RELAXED, __HIP_MEMORY_SCOPE_AGENT); }
; #define XB_SPIN(cond, bar) do { unsigned _sp = 0; while (cond) { __builtin_amdgcn_s_sleep(1); \
;     if ((++_sp & 255u) == 0u) { if (xb_ld(&(bar)[XB_TMO])) break; if (_sp > XB_SPIN_CAP) { atomicAdd(&(bar)[XB_TMO], 1u); break; } } } } while (0)
; __device__ __forceinline__ void xcd_barrier(unsigned* bar, volatile LAS unsigned* st, bool tid0) {
;     ...
;             else XB_SPIN(xb_ld(&bar[XB_TOPGEN]) == tg, bar);
;             __builtin_amdgcn_fence(__ATOMIC_ACQUIRE, "agent");
;             xb_add(&bar[XB_XGEN(x)], 1u);
;             asm volatile("s_waitcnt vmcnt(0)" ::: "memory");
.LBB0_78:
	s_or_b64 exec, exec, s[6:7]
	s_mov_b64 s[6:7], exec
	v_mbcnt_lo_u32_b32 v1, s6, 0
	v_mbcnt_hi_u32_b32 v1, s7, v1
	v_cmp_eq_u32_e32 vcc, 0, v1
	s_waitcnt vmcnt(0)
	s_and_saveexec_b64 s[8:9], vcc
	s_cbranch_execz .LBB0_80
	s_bcnt1_i32_b64 s2, s[6:7]
	v_mov_b32_e32 v1, 0x2000
	v_mov_b32_e32 v2, s2
	global_atomic_add v1, v2, s[4:5] offset:1024

; __device__ __forceinline__ unsigned xb_ld(unsigned* p)              { return __hip_atomic_load(p, __ATOMIC_RELAXED, __HIP_MEMORY_SCOPE_AGENT); }
; __device__ __forceinline__ unsigned xb_add(unsigned* p, unsigned v) { return __hip_atomic_fetch_add(p, v, __ATOMIC_RELAXED, __HIP_MEMORY_SCOPE_AGENT); }
; #define XB_SPIN(cond, bar) do { unsigned _sp = 0; while (cond) { __builtin_amdgcn_s_sleep(1); \
;     if ((++_sp & 255u) == 0u) { if (xb_ld(&(bar)[XB_TMO])) break; if (_sp > XB_SPIN_CAP) { atomicAdd(&(bar)[XB_TMO], 1u); break; } } } } while (0)
; __device__ __forceinline__ void xcd_barrier(unsigned* bar, volatile LAS unsigned* st, bool tid0) {
;     ...
;         const unsigned old = xb_add(&bar[XB_XSUB(x)], 1u);
;         const unsigned gen = old / nloc;
;         if (old + 1u == (gen + 1u) * nloc) {
;             __builtin_amdgcn_fence(__ATOMIC_RELEASE, "agent");
;             asm volatile("s_waitcnt vmcnt(0)" ::: "memory");
;             const unsigned og = xb_add(&bar[XB_TOP], 1u);
;             const unsigned tg = og / nx;
;             if (og + 1u == (tg + 1u) * nx) xb_add(&bar[XB_TOPGEN], 1u);
;             else XB_SPIN(xb_ld(&bar[XB_TOPGEN]) == tg, bar);
;             __builtin_amdgcn_fence(__ATOMIC_ACQUIRE, "agent");
;             xb_add(&bar[XB_XGEN(x)], 1u);
;             asm volatile("s_waitcnt vmcnt(0)" ::: "memory");
;         } else {
;             XB_SPIN(xb_ld(&bar[XB_XGEN(x)]) == gen, bar);
;             __builtin_amdgcn_fence(__ATOMIC_ACQUIRE, "agent");
;             asm volatile("s_waitcnt vmcnt(0)" ::: "memory");
.LBB0_189:
	s_or_b64 exec, exec, s[8:9]
	v_cvt_f32_u32_e32 v4, v2
	s_waitcnt vmcnt(0)
	v_readfirstlane_b32 s2, v3
	v_sub_u32_e32 v3, 0, v2
	v_rcp_iflag_f32_e32 v4, v4
	v_add_u32_e32 v5, s2, v1
	v_mul_f32_e32 v4, 0x4f7ffffe, v4
	v_cvt_u32_f32_e32 v4, v4
	v_mul_lo_u32 v1, v3, v4
	v_mul_hi_u32 v1, v4, v1
	v_add_u32_e32 v1, v4, v1
	v_mul_hi_u32 v1, v5, v1
	v_mul_lo_u32 v3, v1, v2
	v_sub_u32_e32 v3, v5, v3
	v_add_u32_e32 v4, 1, v1
	v_cmp_ge_u32_e32 vcc, v3, v2
	s_nop 1
	v_cndmask_b32_e32 v1, v1, v4, vcc
	v_sub_u32_e32 v4, v3, v2
	v_cndmask_b32_e32 v3, v3, v4, vcc
	v_add_u32_e32 v4, 1, v1
	v_cmp_ge_u32_e32 vcc, v3, v2
	v_add_u32_e32 v3, 1, v5
	s_nop 0
	v_cndmask_b32_e32 v1, v1, v4, vcc
	v_mul_lo_u32 v4, v2, v1
	v_add_u32_e32 v2, v4, v2
	v_cmp_ne_u32_e32 vcc, v3, v2
	s_and_saveexec_b64 s[2:3], vcc
	s_xor_b64 s[6:7], exec, s[2:3]
	s_cbranch_execz .LBB0_203
	s_waitcnt lgkmcnt(0)
	v_mov_b32_e32 v0, 0x2000
	buffer_inv sc1
	global_load_dword v0, v0, s[4:5] offset:1024 sc1
	s_add_u32 s10, s4, 0x2400
	s_addc_u32 s11, s5, 0
	s_waitcnt vmcnt(0)
	v_cmp_eq_u32_e32 vcc, v0, v1
	s_and_saveexec_b64 s[8:9], vcc
	s_cbranch_execz .LBB0_202
	s_mov_b32 s2, 1
	s_mov_b64 s[12:13], 0
	v_mov_b32_e32 v0, 0
	s_branch .LBB0_193

; __device__ __forceinline__ unsigned xb_add(unsigned* p, unsigned v) { return __hip_atomic_fetch_add(p, v, __ATOMIC_RELAXED, __HIP_MEMORY_SCOPE_AGENT); }
; __device__ __forceinline__ void xcd_barrier(unsigned* bar, volatile LAS unsigned* st, bool tid0) {
;     ...
;         if (old + 1u == (gen + 1u) * nloc) {
;             __builtin_amdgcn_fence(__ATOMIC_RELEASE, "agent");
;             asm volatile("s_waitcnt vmcnt(0)" ::: "memory");
;             const unsigned og = xb_add(&bar[XB_TOP], 1u);
.LBB0_203:
	s_andn2_saveexec_b64 s[6:7], s[6:7]
	s_cbranch_execz .LBB0_223
	s_mov_b64 s[8:9], exec
	buffer_wbl2 sc1
	buffer_inv sc1
	s_waitcnt lgkmcnt(0)
	s_waitcnt vmcnt(0)
	v_mbcnt_lo_u32_b32 v1, s8, 0
	v_mbcnt_hi_u32_b32 v1, s9, v1
	v_cmp_eq_u32_e32 vcc, 0, v1
	s_and_saveexec_b64 s[10:11], vcc
	s_cbranch_execz .LBB0_206
	s_bcnt1_i32_b64 s2, s[8:9]
	v_mov_b32_e32 v2, 0x3000
	v_mov_b32_e32 v3, s2
	global_atomic_add v2, v2, v3, s[52:53] offset:1024 sc0

; __device__ __forceinline__ unsigned xb_ld(unsigned* p)              { return __hip_atomic_load(p, __ATOMIC_RELAXED, __HIP_MEMORY_SCOPE_AGENT); }
; __device__ __forceinline__ unsigned xb_add(unsigned* p, unsigned v) { return __hip_atomic_fetch_add(p, v, __ATOMIC_RELAXED, __HIP_MEMORY_SCOPE_AGENT); }
; #define XB_SPIN(cond, bar) do { unsigned _sp = 0; while (cond) { __builtin_amdgcn_s_sleep(1); \
;     if ((++_sp & 255u) == 0u) { if (xb_ld(&(bar)[XB_TMO])) break; if (_sp > XB_SPIN_CAP) { atomicAdd(&(bar)[XB_TMO], 1u); break; } } } } while (0)
; __device__ __forceinline__ void xcd_barrier(unsigned* bar, volatile LAS unsigned* st, bool tid0) {
;     ...
;             else XB_SPIN(xb_ld(&bar[XB_TOPGEN]) == tg, bar);
;             __builtin_amdgcn_fence(__ATOMIC_ACQUIRE, "agent");
;             xb_add(&bar[XB_XGEN(x)], 1u);
;             asm volatile("s_waitcnt vmcnt(0)" ::: "memory");
.LBB0_220:
	s_or_b64 exec, exec, s[8:9]
	s_mov_b64 s[8:9], exec
	v_mbcnt_lo_u32_b32 v0, s8, 0
	v_mbcnt_hi_u32_b32 v0, s9, v0
	v_cmp_eq_u32_e32 vcc, 0, v0
	s_waitcnt vmcnt(0)
	s_and_saveexec_b64 s[10:11], vcc
	s_cbranch_execz .LBB0_222
	s_bcnt1_i32_b64 s2, s[8:9]
	v_mov_b32_e32 v0, 0x2000
	v_mov_b32_e32 v1, s2
	global_atomic_add v0, v1, s[4:5] offset:1024

; __device__ __forceinline__ unsigned xb_ld(unsigned* p)              { return __hip_atomic_load(p, __ATOMIC_RELAXED, __HIP_MEMORY_SCOPE_AGENT); }
; __device__ __forceinline__ unsigned xb_add(unsigned* p, unsigned v) { return __hip_atomic_fetch_add(p, v, __ATOMIC_RELAXED, __HIP_MEMORY_SCOPE_AGENT); }
; #define XB_SPIN(cond, bar) do { unsigned _sp = 0; while (cond) { __builtin_amdgcn_s_sleep(1); \
;     if ((++_sp & 255u) == 0u) { if (xb_ld(&(bar)[XB_TMO])) break; if (_sp > XB_SPIN_CAP) { atomicAdd(&(bar)[XB_TMO], 1u); break; } } } } while (0)
; __device__ __forceinline__ void xcd_barrier(unsigned* bar, volatile LAS unsigned* st, bool tid0) {
;     ...
;         const unsigned old = xb_add(&bar[XB_XSUB(x)], 1u);
;         const unsigned gen = old / nloc;
;         if (old + 1u == (gen + 1u) * nloc) {
;             __builtin_amdgcn_fence(__ATOMIC_RELEASE, "agent");
;             asm volatile("s_waitcnt vmcnt(0)" ::: "memory");
;             const unsigned og = xb_add(&bar[XB_TOP], 1u);
;             const unsigned tg = og / nx;
;             if (og + 1u == (tg + 1u) * nx) xb_add(&bar[XB_TOPGEN], 1u);
;             else XB_SPIN(xb_ld(&bar[XB_TOPGEN]) == tg, bar);
;             __builtin_amdgcn_fence(__ATOMIC_ACQUIRE, "agent");
;             xb_add(&bar[XB_XGEN(x)], 1u);
;             asm volatile("s_waitcnt vmcnt(0)" ::: "memory");
;         } else {
;             XB_SPIN(xb_ld(&bar[XB_XGEN(x)]) == gen, bar);
;             __builtin_amdgcn_fence(__ATOMIC_ACQUIRE, "agent");
;             asm volatile("s_waitcnt vmcnt(0)" ::: "memory");
.LBB0_253:
	s_or_b64 exec, exec, s[8:9]
	v_cvt_f32_u32_e32 v4, v2
	s_waitcnt vmcnt(0)
	v_readfirstlane_b32 s3, v3
	v_sub_u32_e32 v3, 0, v2
	v_rcp_iflag_f32_e32 v4, v4
	v_add_u32_e32 v5, s3, v1
	v_mul_f32_e32 v4, 0x4f7ffffe, v4
	v_cvt_u32_f32_e32 v4, v4
	v_mul_lo_u32 v1, v3, v4
	v_mul_hi_u32 v1, v4, v1
	v_add_u32_e32 v1, v4, v1
	v_mul_hi_u32 v1, v5, v1
	v_mul_lo_u32 v3, v1, v2
	v_sub_u32_e32 v3, v5, v3
	v_add_u32_e32 v4, 1, v1
	v_cmp_ge_u32_e32 vcc, v3, v2
	s_nop 1
	v_cndmask_b32_e32 v1, v1, v4, vcc
	v_sub_u32_e32 v4, v3, v2
	v_cndmask_b32_e32 v3, v3, v4, vcc
	v_add_u32_e32 v4, 1, v1
	v_cmp_ge_u32_e32 vcc, v3, v2
	v_add_u32_e32 v3, 1, v5
	s_nop 0
	v_cndmask_b32_e32 v1, v1, v4, vcc
	v_mul_lo_u32 v4, v2, v1
	v_add_u32_e32 v2, v4, v2
	v_cmp_ne_u32_e32 vcc, v3, v2
	s_and_saveexec_b64 s[6:7], vcc
	s_xor_b64 s[6:7], exec, s[6:7]
	s_cbranch_execz .LBB0_267
	s_waitcnt lgkmcnt(0)
	v_mov_b32_e32 v0, 0x2000
	buffer_inv sc1
	global_load_dword v0, v0, s[4:5] offset:1024 sc1
	s_add_u32 s10, s4, 0x2400
	s_addc_u32 s11, s5, 0
	s_waitcnt vmcnt(0)
	v_cmp_eq_u32_e32 vcc, v0, v1
	s_and_saveexec_b64 s[8:9], vcc
	s_cbranch_execz .LBB0_266
	s_mov_b32 s3, 1
	s_mov_b64 s[16:17], 0
	v_mov_b32_e32 v0, 0
	s_branch .LBB0_257

; __device__ __forceinline__ unsigned xb_add(unsigned* p, unsigned v) { return __hip_atomic_fetch_add(p, v, __ATOMIC_RELAXED, __HIP_MEMORY_SCOPE_AGENT); }
; __device__ __forceinline__ void xcd_barrier(unsigned* bar, volatile LAS unsigned* st, bool tid0) {
;     ...
;         if (old + 1u == (gen + 1u) * nloc) {
;             __builtin_amdgcn_fence(__ATOMIC_RELEASE, "agent");
;             asm volatile("s_waitcnt vmcnt(0)" ::: "memory");
;             const unsigned og = xb_add(&bar[XB_TOP], 1u);
.LBB0_267:
	s_andn2_saveexec_b64 s[6:7], s[6:7]
	s_cbranch_execz .LBB0_287
	s_mov_b64 s[8:9], exec
	buffer_wbl2 sc1
	buffer_inv sc1
	s_waitcnt lgkmcnt(0)
	s_waitcnt vmcnt(0)
	v_mbcnt_lo_u32_b32 v1, s8, 0
	v_mbcnt_hi_u32_b32 v1, s9, v1
	v_cmp_eq_u32_e32 vcc, 0, v1
	s_and_saveexec_b64 s[10:11], vcc
	s_cbranch_execz .LBB0_270
	s_bcnt1_i32_b64 s3, s[8:9]
	v_mov_b32_e32 v2, 0x3000
	v_mov_b32_e32 v3, s3
	global_atomic_add v2, v2, v3, s[52:53] offset:1024 sc0

; __device__ __forceinline__ unsigned xb_ld(unsigned* p)              { return __hip_atomic_load(p, __ATOMIC_RELAXED, __HIP_MEMORY_SCOPE_AGENT); }
; __device__ __forceinline__ unsigned xb_add(unsigned* p, unsigned v) { return __hip_atomic_fetch_add(p, v, __ATOMIC_RELAXED, __HIP_MEMORY_SCOPE_AGENT); }
; #define XB_SPIN(cond, bar) do { unsigned _sp = 0; while (cond) { __builtin_amdgcn_s_sleep(1); \
;     if ((++_sp & 255u) == 0u) { if (xb_ld(&(bar)[XB_TMO])) break; if (_sp > XB_SPIN_CAP) { atomicAdd(&(bar)[XB_TMO], 1u); break; } } } } while (0)
; __device__ __forceinline__ void xcd_barrier(unsigned* bar, volatile LAS unsigned* st, bool tid0) {
;     ...
;             else XB_SPIN(xb_ld(&bar[XB_TOPGEN]) == tg, bar);
;             __builtin_amdgcn_fence(__ATOMIC_ACQUIRE, "agent");
;             xb_add(&bar[XB_XGEN(x)], 1u);
;             asm volatile("s_waitcnt vmcnt(0)" ::: "memory");
.LBB0_284:
	s_or_b64 exec, exec, s[8:9]
	s_mov_b64 s[8:9], exec
	v_mbcnt_lo_u32_b32 v0, s8, 0
	v_mbcnt_hi_u32_b32 v0, s9, v0
	v_cmp_eq_u32_e32 vcc, 0, v0
	s_waitcnt vmcnt(0)
	s_and_saveexec_b64 s[10:11], vcc
	s_cbranch_execz .LBB0_286
	s_bcnt1_i32_b64 s3, s[8:9]
	v_mov_b32_e32 v0, 0x2000
	v_mov_b32_e32 v1, s3
	global_atomic_add v0, v1, s[4:5] offset:1024

; __device__ __forceinline__ unsigned xb_add(unsigned* p, unsigned v) { return __hip_atomic_fetch_add(p, v, __ATOMIC_RELAXED, __HIP_MEMORY_SCOPE_AGENT); }
; __device__ __forceinline__ void xcd_barrier(unsigned* bar, volatile LAS unsigned* st, bool tid0) {
;     ...
;         if (old + 1u == (gen + 1u) * nloc) {
;             __builtin_amdgcn_fence(__ATOMIC_RELEASE, "agent");
;             asm volatile("s_waitcnt vmcnt(0)" ::: "memory");
;             const unsigned og = xb_add(&bar[XB_TOP], 1u);
.LBB0_325:
	s_andn2_saveexec_b64 s[6:7], s[6:7]
	s_cbranch_execz .LBB0_345
	s_mov_b64 s[6:7], exec
	buffer_wbl2 sc1
	buffer_inv sc1
	s_waitcnt lgkmcnt(0)
	s_waitcnt vmcnt(0)
	v_mbcnt_lo_u32_b32 v1, s6, 0
	v_mbcnt_hi_u32_b32 v1, s7, v1
	v_cmp_eq_u32_e32 vcc, 0, v1
	s_and_saveexec_b64 s[8:9], vcc
	s_cbranch_execz .LBB0_328
	s_bcnt1_i32_b64 s3, s[6:7]
	v_mov_b32_e32 v2, 0x3000
	v_mov_b32_e32 v3, s3
	global_atomic_add v2, v2, v3, s[52:53] offset:1024 sc0

; __device__ __forceinline__ unsigned xb_ld(unsigned* p)              { return __hip_atomic_load(p, __ATOMIC_RELAXED, __HIP_MEMORY_SCOPE_AGENT); }
; __device__ __forceinline__ unsigned xb_add(unsigned* p, unsigned v) { return __hip_atomic_fetch_add(p, v, __ATOMIC_RELAXED, __HIP_MEMORY_SCOPE_AGENT); }
; #define XB_SPIN(cond, bar) do { unsigned _sp = 0; while (cond) { __builtin_amdgcn_s_sleep(1); \
;     if ((++_sp & 255u) == 0u) { if (xb_ld(&(bar)[XB_TMO])) break; if (_sp > XB_SPIN_CAP) { atomicAdd(&(bar)[XB_TMO], 1u); break; } } } } while (0)
; __device__ __forceinline__ void xcd_barrier(unsigned* bar, volatile LAS unsigned* st, bool tid0) {
;     ...
;             else XB_SPIN(xb_ld(&bar[XB_TOPGEN]) == tg, bar);
;             __builtin_amdgcn_fence(__ATOMIC_ACQUIRE, "agent");
;             xb_add(&bar[XB_XGEN(x)], 1u);
;             asm volatile("s_waitcnt vmcnt(0)" ::: "memory");
.LBB0_342:
	s_or_b64 exec, exec, s[6:7]
	s_mov_b64 s[6:7], exec
	v_mbcnt_lo_u32_b32 v0, s6, 0
	v_mbcnt_hi_u32_b32 v0, s7, v0
	v_cmp_eq_u32_e32 vcc, 0, v0
	s_waitcnt vmcnt(0)
	s_and_saveexec_b64 s[8:9], vcc
	s_cbranch_execz .LBB0_344
	s_bcnt1_i32_b64 s3, s[6:7]
	v_mov_b32_e32 v0, 0x2000
	v_mov_b32_e32 v1, s3
	global_atomic_add v0, v1, s[4:5] offset:1024

; __device__ __forceinline__ unsigned xb_add(unsigned* p, unsigned v) { return __hip_atomic_fetch_add(p, v, __ATOMIC_RELAXED, __HIP_MEMORY_SCOPE_AGENT); }
; __device__ __forceinline__ void xcd_barrier(unsigned* bar, volatile LAS unsigned* st, bool tid0) {
;     ...
;         if (old + 1u == (gen + 1u) * nloc) {
;             __builtin_amdgcn_fence(__ATOMIC_RELEASE, "agent");
;             asm volatile("s_waitcnt vmcnt(0)" ::: "memory");
;             const unsigned og = xb_add(&bar[XB_TOP], 1u);
.LBB0_476:
	s_andn2_saveexec_b64 s[2:3], s[6:7]
	s_cbranch_execz .LBB0_496
	s_mov_b64 s[6:7], exec
	buffer_wbl2 sc1
	buffer_inv sc1
	s_waitcnt lgkmcnt(0)
	s_waitcnt vmcnt(0)
	v_mbcnt_lo_u32_b32 v1, s6, 0
	v_mbcnt_hi_u32_b32 v1, s7, v1
	v_cmp_eq_u32_e32 vcc, 0, v1
	s_and_saveexec_b64 s[8:9], vcc
	s_cbranch_execz .LBB0_479
	s_bcnt1_i32_b64 s2, s[6:7]
	v_mov_b32_e32 v2, 0x3000
	v_mov_b32_e32 v3, s2
	global_atomic_add v2, v2, v3, s[52:53] offset:1024 sc0

; __device__ __forceinline__ unsigned xb_ld(unsigned* p)              { return __hip_atomic_load(p, __ATOMIC_RELAXED, __HIP_MEMORY_SCOPE_AGENT); }
; __device__ __forceinline__ unsigned xb_add(unsigned* p, unsigned v) { return __hip_atomic_fetch_add(p, v, __ATOMIC_RELAXED, __HIP_MEMORY_SCOPE_AGENT); }
; #define XB_SPIN(cond, bar) do { unsigned _sp = 0; while (cond) { __builtin_amdgcn_s_sleep(1); \
;     if ((++_sp & 255u) == 0u) { if (xb_ld(&(bar)[XB_TMO])) break; if (_sp > XB_SPIN_CAP) { atomicAdd(&(bar)[XB_TMO], 1u); break; } } } } while (0)
; __device__ __forceinline__ void xcd_barrier(unsigned* bar, volatile LAS unsigned* st, bool tid0) {
;     ...
;             else XB_SPIN(xb_ld(&bar[XB_TOPGEN]) == tg, bar);
;             __builtin_amdgcn_fence(__ATOMIC_ACQUIRE, "agent");
;             xb_add(&bar[XB_XGEN(x)], 1u);
;             asm volatile("s_waitcnt vmcnt(0)" ::: "memory");
.LBB0_493:
	s_or_b64 exec, exec, s[6:7]
	s_mov_b64 s[6:7], exec
	v_mbcnt_lo_u32_b32 v0, s6, 0
	v_mbcnt_hi_u32_b32 v0, s7, v0
	v_cmp_eq_u32_e32 vcc, 0, v0
	s_waitcnt vmcnt(0)
	s_and_saveexec_b64 s[8:9], vcc
	s_cbranch_execz .LBB0_495
	s_bcnt1_i32_b64 s2, s[6:7]
	v_mov_b32_e32 v0, 0x2000
	v_mov_b32_e32 v1, s2
	global_atomic_add v0, v1, s[4:5] offset:1024

; __device__ __forceinline__ unsigned xb_ld(unsigned* p)              { return __hip_atomic_load(p, __ATOMIC_RELAXED, __HIP_MEMORY_SCOPE_AGENT); }
; __device__ __forceinline__ unsigned xb_add(unsigned* p, unsigned v) { return __hip_atomic_fetch_add(p, v, __ATOMIC_RELAXED, __HIP_MEMORY_SCOPE_AGENT); }
; #define XB_SPIN(cond, bar) do { unsigned _sp = 0; while (cond) { __builtin_amdgcn_s_sleep(1); \
;     if ((++_sp & 255u) == 0u) { if (xb_ld(&(bar)[XB_TMO])) break; if (_sp > XB_SPIN_CAP) { atomicAdd(&(bar)[XB_TMO], 1u); break; } } } } while (0)
; __device__ __forceinline__ void xcd_barrier(unsigned* bar, volatile LAS unsigned* st, bool tid0) {
;     ...
;         const unsigned old = xb_add(&bar[XB_XSUB(x)], 1u);
;         const unsigned gen = old / nloc;
;         if (old + 1u == (gen + 1u) * nloc) {
;             __builtin_amdgcn_fence(__ATOMIC_RELEASE, "agent");
;             asm volatile("s_waitcnt vmcnt(0)" ::: "memory");
;             const unsigned og = xb_add(&bar[XB_TOP], 1u);
;             const unsigned tg = og / nx;
;             if (og + 1u == (tg + 1u) * nx) xb_add(&bar[XB_TOPGEN], 1u);
;             else XB_SPIN(xb_ld(&bar[XB_TOPGEN]) == tg, bar);
;             __builtin_amdgcn_fence(__ATOMIC_ACQUIRE, "agent");
;             xb_add(&bar[XB_XGEN(x)], 1u);
;             asm volatile("s_waitcnt vmcnt(0)" ::: "memory");
;         } else {
;             XB_SPIN(xb_ld(&bar[XB_XGEN(x)]) == gen, bar);
;             __builtin_amdgcn_fence(__ATOMIC_ACQUIRE, "agent");
;             asm volatile("s_waitcnt vmcnt(0)" ::: "memory");
.LBB0_570:
	s_or_b64 exec, exec, s[12:13]
	v_cvt_f32_u32_e32 v4, v2
	s_waitcnt vmcnt(0)
	v_readfirstlane_b32 s2, v3
	v_sub_u32_e32 v3, 0, v2
	v_rcp_iflag_f32_e32 v4, v4
	v_add_u32_e32 v5, s2, v1
	v_mul_f32_e32 v4, 0x4f7ffffe, v4
	v_cvt_u32_f32_e32 v4, v4
	v_mul_lo_u32 v1, v3, v4
	v_mul_hi_u32 v1, v4, v1
	v_add_u32_e32 v1, v4, v1
	v_mul_hi_u32 v1, v5, v1
	v_mul_lo_u32 v3, v1, v2
	v_sub_u32_e32 v3, v5, v3
	v_add_u32_e32 v4, 1, v1
	v_cmp_ge_u32_e32 vcc, v3, v2
	s_nop 1
	v_cndmask_b32_e32 v1, v1, v4, vcc
	v_sub_u32_e32 v4, v3, v2
	v_cndmask_b32_e32 v3, v3, v4, vcc
	v_add_u32_e32 v4, 1, v1
	v_cmp_ge_u32_e32 vcc, v3, v2
	v_add_u32_e32 v3, 1, v5
	s_nop 0
	v_cndmask_b32_e32 v1, v1, v4, vcc
	v_mul_lo_u32 v4, v2, v1
	v_add_u32_e32 v2, v4, v2
	v_cmp_ne_u32_e32 vcc, v3, v2
	s_and_saveexec_b64 s[2:3], vcc
	s_xor_b64 s[10:11], exec, s[2:3]
	s_cbranch_execz .LBB0_584
	s_waitcnt lgkmcnt(0)
	v_mov_b32_e32 v0, 0x2000
	buffer_inv sc1
	global_load_dword v0, v0, s[6:7] offset:1024 sc1
	s_add_u32 s14, s6, 0x2400
	s_addc_u32 s15, s7, 0
	s_waitcnt vmcnt(0)
	v_cmp_eq_u32_e32 vcc, v0, v1
	s_and_saveexec_b64 s[12:13], vcc
	s_cbranch_execz .LBB0_583
	s_mov_b32 s2, 1
	s_mov_b64 s[16:17], 0
	v_mov_b32_e32 v0, 0
	s_branch .LBB0_574

; __device__ __forceinline__ unsigned xb_ld(unsigned* p)              { return __hip_atomic_load(p, __ATOMIC_RELAXED, __HIP_MEMORY_SCOPE_AGENT); }
; __device__ __forceinline__ unsigned xb_add(unsigned* p, unsigned v) { return __hip_atomic_fetch_add(p, v, __ATOMIC_RELAXED, __HIP_MEMORY_SCOPE_AGENT); }
; #define XB_SPIN(cond, bar) do { unsigned _sp = 0; while (cond) { __builtin_amdgcn_s_sleep(1); \
;     if ((++_sp & 255u) == 0u) { if (xb_ld(&(bar)[XB_TMO])) break; if (_sp > XB_SPIN_CAP) { atomicAdd(&(bar)[XB_TMO], 1u); break; } } } } while (0)
; __device__ __forceinline__ void xcd_barrier(unsigned* bar, volatile LAS unsigned* st, bool tid0) {
;     ...
;         if (old + 1u == (gen + 1u) * nloc) {
;             __builtin_amdgcn_fence(__ATOMIC_RELEASE, "agent");
;             asm volatile("s_waitcnt vmcnt(0)" ::: "memory");
;             const unsigned og = xb_add(&bar[XB_TOP], 1u);
;             const unsigned tg = og / nx;
;             if (og + 1u == (tg + 1u) * nx) xb_add(&bar[XB_TOPGEN], 1u);
;             else XB_SPIN(xb_ld(&bar[XB_TOPGEN]) == tg, bar);
;             __builtin_amdgcn_fence(__ATOMIC_ACQUIRE, "agent");
;             xb_add(&bar[XB_XGEN(x)], 1u);
;             asm volatile("s_waitcnt vmcnt(0)" ::: "memory");
;         } else {
;             XB_SPIN(xb_ld(&bar[XB_XGEN(x)]) == gen, bar);
;             __builtin_amdgcn_fence(__ATOMIC_ACQUIRE, "agent");
;             asm volatile("s_waitcnt vmcnt(0)" ::: "memory");
.LBB0_583:
	s_or_b64 exec, exec, s[12:13]
	s_waitcnt vmcnt(0)
	s_waitcnt vmcnt(0)
.LBB0_584:
	s_andn2_saveexec_b64 s[10:11], s[10:11]
	s_cbranch_execz .LBB0_604
	s_mov_b64 s[12:13], exec
	buffer_wbl2 sc1
	buffer_inv sc1
	s_waitcnt lgkmcnt(0)
	s_waitcnt vmcnt(0)
	v_mbcnt_lo_u32_b32 v1, s12, 0
	v_mbcnt_hi_u32_b32 v1, s13, v1
	v_cmp_eq_u32_e32 vcc, 0, v1
	s_and_saveexec_b64 s[14:15], vcc
	s_cbranch_execz .LBB0_587
	s_bcnt1_i32_b64 s2, s[12:13]
	v_mov_b32_e32 v2, 0x3000
	v_mov_b32_e32 v3, s2
	global_atomic_add v2, v2, v3, s[52:53] offset:1024 sc0

; __device__ __forceinline__ unsigned xb_ld(unsigned* p)              { return __hip_atomic_load(p, __ATOMIC_RELAXED, __HIP_MEMORY_SCOPE_AGENT); }
; __device__ __forceinline__ unsigned xb_add(unsigned* p, unsigned v) { return __hip_atomic_fetch_add(p, v, __ATOMIC_RELAXED, __HIP_MEMORY_SCOPE_AGENT); }
; #define XB_SPIN(cond, bar) do { unsigned _sp = 0; while (cond) { __builtin_amdgcn_s_sleep(1); \
;     if ((++_sp & 255u) == 0u) { if (xb_ld(&(bar)[XB_TMO])) break; if (_sp > XB_SPIN_CAP) { atomicAdd(&(bar)[XB_TMO], 1u); break; } } } } while (0)
; __device__ __forceinline__ void xcd_barrier(unsigned* bar, volatile LAS unsigned* st, bool tid0) {
;     ...
;             else XB_SPIN(xb_ld(&bar[XB_TOPGEN]) == tg, bar);
;             __builtin_amdgcn_fence(__ATOMIC_ACQUIRE, "agent");
;             xb_add(&bar[XB_XGEN(x)], 1u);
;             asm volatile("s_waitcnt vmcnt(0)" ::: "memory");
.LBB0_601:
	s_or_b64 exec, exec, s[12:13]
	s_mov_b64 s[12:13], exec
	v_mbcnt_lo_u32_b32 v0, s12, 0
	v_mbcnt_hi_u32_b32 v0, s13, v0
	v_cmp_eq_u32_e32 vcc, 0, v0
	s_waitcnt vmcnt(0)
	s_and_saveexec_b64 s[14:15], vcc
	s_cbranch_execz .LBB0_603
	s_bcnt1_i32_b64 s2, s[12:13]
	v_mov_b32_e32 v0, 0x2000
	v_mov_b32_e32 v1, s2
	global_atomic_add v0, v1, s[6:7] offset:1024

; __device__ __forceinline__ unsigned xb_ld(unsigned* p)              { return __hip_atomic_load(p, __ATOMIC_RELAXED, __HIP_MEMORY_SCOPE_AGENT); }
; __device__ __forceinline__ unsigned xb_add(unsigned* p, unsigned v) { return __hip_atomic_fetch_add(p, v, __ATOMIC_RELAXED, __HIP_MEMORY_SCOPE_AGENT); }
; #define XB_SPIN(cond, bar) do { unsigned _sp = 0; while (cond) { __builtin_amdgcn_s_sleep(1); \
;     if ((++_sp & 255u) == 0u) { if (xb_ld(&(bar)[XB_TMO])) break; if (_sp > XB_SPIN_CAP) { atomicAdd(&(bar)[XB_TMO], 1u); break; } } } } while (0)
; __device__ __forceinline__ void xcd_barrier(unsigned* bar, volatile LAS unsigned* st, bool tid0) {
;     ...
;         const unsigned old = xb_add(&bar[XB_XSUB(x)], 1u);
;         const unsigned gen = old / nloc;
;         if (old + 1u == (gen + 1u) * nloc) {
;             __builtin_amdgcn_fence(__ATOMIC_RELEASE, "agent");
;             asm volatile("s_waitcnt vmcnt(0)" ::: "memory");
;             const unsigned og = xb_add(&bar[XB_TOP], 1u);
;             const unsigned tg = og / nx;
;             if (og + 1u == (tg + 1u) * nx) xb_add(&bar[XB_TOPGEN], 1u);
;             else XB_SPIN(xb_ld(&bar[XB_TOPGEN]) == tg, bar);
;             __builtin_amdgcn_fence(__ATOMIC_ACQUIRE, "agent");
;             xb_add(&bar[XB_XGEN(x)], 1u);
;             asm volatile("s_waitcnt vmcnt(0)" ::: "memory");
;         } else {
;             XB_SPIN(xb_ld(&bar[XB_XGEN(x)]) == gen, bar);
;             __builtin_amdgcn_fence(__ATOMIC_ACQUIRE, "agent");
;             asm volatile("s_waitcnt vmcnt(0)" ::: "memory");
.LBB0_661:
	s_or_b64 exec, exec, s[12:13]
	v_cvt_f32_u32_e32 v4, v2
	s_waitcnt vmcnt(0)
	v_readfirstlane_b32 s2, v3
	v_sub_u32_e32 v3, 0, v2
	v_rcp_iflag_f32_e32 v4, v4
	v_add_u32_e32 v5, s2, v1
	v_mul_f32_e32 v4, 0x4f7ffffe, v4
	v_cvt_u32_f32_e32 v4, v4
	v_mul_lo_u32 v1, v3, v4
	v_mul_hi_u32 v1, v4, v1
	v_add_u32_e32 v1, v4, v1
	v_mul_hi_u32 v1, v5, v1
	v_mul_lo_u32 v3, v1, v2
	v_sub_u32_e32 v3, v5, v3
	v_add_u32_e32 v4, 1, v1
	v_cmp_ge_u32_e32 vcc, v3, v2
	s_nop 1
	v_cndmask_b32_e32 v1, v1, v4, vcc
	v_sub_u32_e32 v4, v3, v2
	v_cndmask_b32_e32 v3, v3, v4, vcc
	v_add_u32_e32 v4, 1, v1
	v_cmp_ge_u32_e32 vcc, v3, v2
	v_add_u32_e32 v3, 1, v5
	s_nop 0
	v_cndmask_b32_e32 v1, v1, v4, vcc
	v_mul_lo_u32 v4, v2, v1
	v_add_u32_e32 v2, v4, v2
	v_cmp_ne_u32_e32 vcc, v3, v2
	s_and_saveexec_b64 s[2:3], vcc
	s_xor_b64 s[8:9], exec, s[2:3]
	s_cbranch_execz .LBB0_675
	s_waitcnt lgkmcnt(0)
	v_mov_b32_e32 v0, 0x2000
	buffer_inv sc1
	global_load_dword v0, v0, s[6:7] offset:1024 sc1
	s_add_u32 s14, s6, 0x2400
	s_addc_u32 s15, s7, 0
	s_waitcnt vmcnt(0)
	v_cmp_eq_u32_e32 vcc, v0, v1
	s_and_saveexec_b64 s[12:13], vcc
	s_cbranch_execz .LBB0_674
	s_mov_b32 s2, 1
	s_mov_b64 s[16:17], 0
	v_mov_b32_e32 v0, 0
	s_branch .LBB0_665

; __device__ __forceinline__ unsigned xb_add(unsigned* p, unsigned v) { return __hip_atomic_fetch_add(p, v, __ATOMIC_RELAXED, __HIP_MEMORY_SCOPE_AGENT); }
; __device__ __forceinline__ void xcd_barrier(unsigned* bar, volatile LAS unsigned* st, bool tid0) {
;     ...
;         if (old + 1u == (gen + 1u) * nloc) {
;             __builtin_amdgcn_fence(__ATOMIC_RELEASE, "agent");
;             asm volatile("s_waitcnt vmcnt(0)" ::: "memory");
;             const unsigned og = xb_add(&bar[XB_TOP], 1u);
.LBB0_675:
	s_andn2_saveexec_b64 s[8:9], s[8:9]
	s_cbranch_execz .LBB0_695
	s_mov_b64 s[12:13], exec
	buffer_wbl2 sc1
	buffer_inv sc1
	s_waitcnt lgkmcnt(0)
	s_waitcnt vmcnt(0)
	v_mbcnt_lo_u32_b32 v1, s12, 0
	v_mbcnt_hi_u32_b32 v1, s13, v1
	v_cmp_eq_u32_e32 vcc, 0, v1
	s_and_saveexec_b64 s[14:15], vcc
	s_cbranch_execz .LBB0_678
	s_bcnt1_i32_b64 s2, s[12:13]
	v_mov_b32_e32 v2, 0x3000
	v_mov_b32_e32 v3, s2
	global_atomic_add v2, v2, v3, s[52:53] offset:1024 sc0

; __device__ __forceinline__ unsigned xb_ld(unsigned* p)              { return __hip_atomic_load(p, __ATOMIC_RELAXED, __HIP_MEMORY_SCOPE_AGENT); }
; __device__ __forceinline__ unsigned xb_add(unsigned* p, unsigned v) { return __hip_atomic_fetch_add(p, v, __ATOMIC_RELAXED, __HIP_MEMORY_SCOPE_AGENT); }
; #define XB_SPIN(cond, bar) do { unsigned _sp = 0; while (cond) { __builtin_amdgcn_s_sleep(1); \
;     if ((++_sp & 255u) == 0u) { if (xb_ld(&(bar)[XB_TMO])) break; if (_sp > XB_SPIN_CAP) { atomicAdd(&(bar)[XB_TMO], 1u); break; } } } } while (0)
; __device__ __forceinline__ void xcd_barrier(unsigned* bar, volatile LAS unsigned* st, bool tid0) {
;     ...
;         const unsigned old = xb_add(&bar[XB_XSUB(x)], 1u);
;         const unsigned gen = old / nloc;
;         if (old + 1u == (gen + 1u) * nloc) {
;             __builtin_amdgcn_fence(__ATOMIC_RELEASE, "agent");
;             asm volatile("s_waitcnt vmcnt(0)" ::: "memory");
;             const unsigned og = xb_add(&bar[XB_TOP], 1u);
;             const unsigned tg = og / nx;
;             if (og + 1u == (tg + 1u) * nx) xb_add(&bar[XB_TOPGEN], 1u);
;             else XB_SPIN(xb_ld(&bar[XB_TOPGEN]) == tg, bar);
;             __builtin_amdgcn_fence(__ATOMIC_ACQUIRE, "agent");
;             xb_add(&bar[XB_XGEN(x)], 1u);
;             asm volatile("s_waitcnt vmcnt(0)" ::: "memory");
;         } else {
;             XB_SPIN(xb_ld(&bar[XB_XGEN(x)]) == gen, bar);
;             __builtin_amdgcn_fence(__ATOMIC_ACQUIRE, "agent");
;             asm volatile("s_waitcnt vmcnt(0)" ::: "memory");
.LBB0_788:
	s_or_b64 exec, exec, s[14:15]
	v_cvt_f32_u32_e32 v4, v2
	s_waitcnt vmcnt(0)
	v_readfirstlane_b32 s2, v3
	v_sub_u32_e32 v3, 0, v2
	v_rcp_iflag_f32_e32 v4, v4
	v_add_u32_e32 v5, s2, v1
	v_mul_f32_e32 v4, 0x4f7ffffe, v4
	v_cvt_u32_f32_e32 v4, v4
	v_mul_lo_u32 v1, v3, v4
	v_mul_hi_u32 v1, v4, v1
	v_add_u32_e32 v1, v4, v1
	v_mul_hi_u32 v1, v5, v1
	v_mul_lo_u32 v3, v1, v2
	v_sub_u32_e32 v3, v5, v3
	v_add_u32_e32 v4, 1, v1
	v_cmp_ge_u32_e32 vcc, v3, v2
	s_nop 1
	v_cndmask_b32_e32 v1, v1, v4, vcc
	v_sub_u32_e32 v4, v3, v2
	v_cndmask_b32_e32 v3, v3, v4, vcc
	v_add_u32_e32 v4, 1, v1
	v_cmp_ge_u32_e32 vcc, v3, v2
	v_add_u32_e32 v3, 1, v5
	s_nop 0
	v_cndmask_b32_e32 v1, v1, v4, vcc
	v_mul_lo_u32 v4, v2, v1
	v_add_u32_e32 v2, v4, v2
	v_cmp_ne_u32_e32 vcc, v3, v2
	s_and_saveexec_b64 s[2:3], vcc
	s_xor_b64 s[8:9], exec, s[2:3]
	s_cbranch_execz .LBB0_802
	s_waitcnt lgkmcnt(0)
	v_mov_b32_e32 v0, 0x2000
	buffer_inv sc1
	global_load_dword v0, v0, s[6:7] offset:1024 sc1
	s_add_u32 s16, s6, 0x2400
	s_addc_u32 s17, s7, 0
	s_waitcnt vmcnt(0)
	v_cmp_eq_u32_e32 vcc, v0, v1
	s_and_saveexec_b64 s[14:15], vcc
	s_cbranch_execz .LBB0_801
	s_mov_b32 s2, 1
	s_mov_b64 s[18:19], 0
	v_mov_b32_e32 v0, 0
	s_branch .LBB0_792

; __device__ __forceinline__ unsigned xb_ld(unsigned* p)              { return __hip_atomic_load(p, __ATOMIC_RELAXED, __HIP_MEMORY_SCOPE_AGENT); }
; __device__ __forceinline__ unsigned xb_add(unsigned* p, unsigned v) { return __hip_atomic_fetch_add(p, v, __ATOMIC_RELAXED, __HIP_MEMORY_SCOPE_AGENT); }
; #define XB_SPIN(cond, bar) do { unsigned _sp = 0; while (cond) { __builtin_amdgcn_s_sleep(1); \
;     if ((++_sp & 255u) == 0u) { if (xb_ld(&(bar)[XB_TMO])) break; if (_sp > XB_SPIN_CAP) { atomicAdd(&(bar)[XB_TMO], 1u); break; } } } } while (0)
; __device__ __forceinline__ void xcd_barrier(unsigned* bar, volatile LAS unsigned* st, bool tid0) {
;     ...
;         if (old + 1u == (gen + 1u) * nloc) {
;             __builtin_amdgcn_fence(__ATOMIC_RELEASE, "agent");
;             asm volatile("s_waitcnt vmcnt(0)" ::: "memory");
;             const unsigned og = xb_add(&bar[XB_TOP], 1u);
;             const unsigned tg = og / nx;
;             if (og + 1u == (tg + 1u) * nx) xb_add(&bar[XB_TOPGEN], 1u);
;             else XB_SPIN(xb_ld(&bar[XB_TOPGEN]) == tg, bar);
;             __builtin_amdgcn_fence(__ATOMIC_ACQUIRE, "agent");
;             xb_add(&bar[XB_XGEN(x)], 1u);
;             asm volatile("s_waitcnt vmcnt(0)" ::: "memory");
;         } else {
;             XB_SPIN(xb_ld(&bar[XB_XGEN(x)]) == gen, bar);
;             __builtin_amdgcn_fence(__ATOMIC_ACQUIRE, "agent");
;             asm volatile("s_waitcnt vmcnt(0)" ::: "memory");
.LBB0_801:
	s_or_b64 exec, exec, s[14:15]
	s_waitcnt vmcnt(0)
	s_waitcnt vmcnt(0)
.LBB0_802:
	s_andn2_saveexec_b64 s[8:9], s[8:9]
	s_cbranch_execz .LBB0_822
	s_mov_b64 s[14:15], exec
	buffer_wbl2 sc1
	buffer_inv sc1
	s_waitcnt lgkmcnt(0)
	s_waitcnt vmcnt(0)
	v_mbcnt_lo_u32_b32 v1, s14, 0
	v_mbcnt_hi_u32_b32 v1, s15, v1
	v_cmp_eq_u32_e32 vcc, 0, v1
	s_and_saveexec_b64 s[16:17], vcc
	s_cbranch_execz .LBB0_805
	s_bcnt1_i32_b64 s2, s[14:15]
	v_mov_b32_e32 v2, 0x3000
	v_mov_b32_e32 v3, s2
	global_atomic_add v2, v2, v3, s[52:53] offset:1024 sc0

; __device__ __forceinline__ unsigned xb_ld(unsigned* p)              { return __hip_atomic_load(p, __ATOMIC_RELAXED, __HIP_MEMORY_SCOPE_AGENT); }
; __device__ __forceinline__ unsigned xb_add(unsigned* p, unsigned v) { return __hip_atomic_fetch_add(p, v, __ATOMIC_RELAXED, __HIP_MEMORY_SCOPE_AGENT); }
; #define XB_SPIN(cond, bar) do { unsigned _sp = 0; while (cond) { __builtin_amdgcn_s_sleep(1); \
;     if ((++_sp & 255u) == 0u) { if (xb_ld(&(bar)[XB_TMO])) break; if (_sp > XB_SPIN_CAP) { atomicAdd(&(bar)[XB_TMO], 1u); break; } } } } while (0)
; __device__ __forceinline__ void xcd_barrier(unsigned* bar, volatile LAS unsigned* st, bool tid0) {
;     ...
;             else XB_SPIN(xb_ld(&bar[XB_TOPGEN]) == tg, bar);
;             __builtin_amdgcn_fence(__ATOMIC_ACQUIRE, "agent");
;             xb_add(&bar[XB_XGEN(x)], 1u);
;             asm volatile("s_waitcnt vmcnt(0)" ::: "memory");
.LBB0_819:
	s_or_b64 exec, exec, s[14:15]
	s_mov_b64 s[14:15], exec
	v_mbcnt_lo_u32_b32 v0, s14, 0
	v_mbcnt_hi_u32_b32 v0, s15, v0
	v_cmp_eq_u32_e32 vcc, 0, v0
	s_waitcnt vmcnt(0)
	s_and_saveexec_b64 s[16:17], vcc
	s_cbranch_execz .LBB0_821
	s_bcnt1_i32_b64 s2, s[14:15]
	v_mov_b32_e32 v0, 0x2000
	v_mov_b32_e32 v1, s2
	global_atomic_add v0, v1, s[6:7] offset:1024

; __device__ __forceinline__ unsigned xb_ld(unsigned* p)              { return __hip_atomic_load(p, __ATOMIC_RELAXED, __HIP_MEMORY_SCOPE_AGENT); }
; __device__ __forceinline__ unsigned xb_add(unsigned* p, unsigned v) { return __hip_atomic_fetch_add(p, v, __ATOMIC_RELAXED, __HIP_MEMORY_SCOPE_AGENT); }
; #define XB_SPIN(cond, bar) do { unsigned _sp = 0; while (cond) { __builtin_amdgcn_s_sleep(1); \
;     if ((++_sp & 255u) == 0u) { if (xb_ld(&(bar)[XB_TMO])) break; if (_sp > XB_SPIN_CAP) { atomicAdd(&(bar)[XB_TMO], 1u); break; } } } } while (0)
; __device__ __forceinline__ void xcd_barrier(unsigned* bar, volatile LAS unsigned* st, bool tid0) {
;     ...
;         const unsigned old = xb_add(&bar[XB_XSUB(x)], 1u);
;         const unsigned gen = old / nloc;
;         if (old + 1u == (gen + 1u) * nloc) {
;             __builtin_amdgcn_fence(__ATOMIC_RELEASE, "agent");
;             asm volatile("s_waitcnt vmcnt(0)" ::: "memory");
;             const unsigned og = xb_add(&bar[XB_TOP], 1u);
;             const unsigned tg = og / nx;
;             if (og + 1u == (tg + 1u) * nx) xb_add(&bar[XB_TOPGEN], 1u);
;             else XB_SPIN(xb_ld(&bar[XB_TOPGEN]) == tg, bar);
;             __builtin_amdgcn_fence(__ATOMIC_ACQUIRE, "agent");
;             xb_add(&bar[XB_XGEN(x)], 1u);
;             asm volatile("s_waitcnt vmcnt(0)" ::: "memory");
;         } else {
;             XB_SPIN(xb_ld(&bar[XB_XGEN(x)]) == gen, bar);
;             __builtin_amdgcn_fence(__ATOMIC_ACQUIRE, "agent");
;             asm volatile("s_waitcnt vmcnt(0)" ::: "memory");
.LBB0_1050:
	s_or_b64 exec, exec, s[6:7]
	v_cvt_f32_u32_e32 v4, v2
	s_waitcnt vmcnt(0)
	v_readfirstlane_b32 s4, v3
	v_sub_u32_e32 v3, 0, v2
	v_rcp_iflag_f32_e32 v4, v4
	v_add_u32_e32 v5, s4, v1
	v_mul_f32_e32 v4, 0x4f7ffffe, v4
	v_cvt_u32_f32_e32 v4, v4
	v_mul_lo_u32 v1, v3, v4
	v_mul_hi_u32 v1, v4, v1
	v_add_u32_e32 v1, v4, v1
	v_mul_hi_u32 v1, v5, v1
	v_mul_lo_u32 v3, v1, v2
	v_sub_u32_e32 v3, v5, v3
	v_add_u32_e32 v4, 1, v1
	v_cmp_ge_u32_e32 vcc, v3, v2
	s_nop 1
	v_cndmask_b32_e32 v1, v1, v4, vcc
	v_sub_u32_e32 v4, v3, v2
	v_cndmask_b32_e32 v3, v3, v4, vcc
	v_add_u32_e32 v4, 1, v1
	v_cmp_ge_u32_e32 vcc, v3, v2
	v_add_u32_e32 v3, 1, v5
	s_nop 0
	v_cndmask_b32_e32 v1, v1, v4, vcc
	v_mul_lo_u32 v4, v2, v1
	v_add_u32_e32 v2, v4, v2
	v_cmp_ne_u32_e32 vcc, v3, v2
	s_and_saveexec_b64 s[4:5], vcc
	s_xor_b64 s[4:5], exec, s[4:5]
	s_cbranch_execz .LBB0_1064
	s_waitcnt lgkmcnt(0)
	v_mov_b32_e32 v0, 0x2000
	buffer_inv sc1
	global_load_dword v0, v0, s[2:3] offset:1024 sc1
	s_add_u32 s8, s2, 0x2400
	s_addc_u32 s9, s3, 0
	s_waitcnt vmcnt(0)
	v_cmp_eq_u32_e32 vcc, v0, v1
	s_and_saveexec_b64 s[6:7], vcc
	s_cbranch_execz .LBB0_1063
	s_mov_b32 s22, 1
	s_mov_b64 s[12:13], 0
	v_mov_b32_e32 v0, 0
	s_branch .LBB0_1054

; __device__ __forceinline__ unsigned xb_ld(unsigned* p)              { return __hip_atomic_load(p, __ATOMIC_RELAXED, __HIP_MEMORY_SCOPE_AGENT); }
; __device__ __forceinline__ unsigned xb_add(unsigned* p, unsigned v) { return __hip_atomic_fetch_add(p, v, __ATOMIC_RELAXED, __HIP_MEMORY_SCOPE_AGENT); }
; #define XB_SPIN(cond, bar) do { unsigned _sp = 0; while (cond) { __builtin_amdgcn_s_sleep(1); \
;     if ((++_sp & 255u) == 0u) { if (xb_ld(&(bar)[XB_TMO])) break; if (_sp > XB_SPIN_CAP) { atomicAdd(&(bar)[XB_TMO], 1u); break; } } } } while (0)
; __device__ __forceinline__ void xcd_barrier(unsigned* bar, volatile LAS unsigned* st, bool tid0) {
;     ...
;         if (old + 1u == (gen + 1u) * nloc) {
;             __builtin_amdgcn_fence(__ATOMIC_RELEASE, "agent");
;             asm volatile("s_waitcnt vmcnt(0)" ::: "memory");
;             const unsigned og = xb_add(&bar[XB_TOP], 1u);
;             const unsigned tg = og / nx;
;             if (og + 1u == (tg + 1u) * nx) xb_add(&bar[XB_TOPGEN], 1u);
;             else XB_SPIN(xb_ld(&bar[XB_TOPGEN]) == tg, bar);
;             __builtin_amdgcn_fence(__ATOMIC_ACQUIRE, "agent");
;             xb_add(&bar[XB_XGEN(x)], 1u);
;             asm volatile("s_waitcnt vmcnt(0)" ::: "memory");
;         } else {
;             XB_SPIN(xb_ld(&bar[XB_XGEN(x)]) == gen, bar);
;             __builtin_amdgcn_fence(__ATOMIC_ACQUIRE, "agent");
;             asm volatile("s_waitcnt vmcnt(0)" ::: "memory");
.LBB0_1063:
	s_or_b64 exec, exec, s[6:7]
	s_waitcnt vmcnt(0)
	s_waitcnt vmcnt(0)
.LBB0_1064:
	s_andn2_saveexec_b64 s[4:5], s[4:5]
	s_cbranch_execz .LBB0_1084
	s_mov_b64 s[6:7], exec
	buffer_wbl2 sc1
	buffer_inv sc1
	s_waitcnt lgkmcnt(0)
	s_waitcnt vmcnt(0)
	v_mbcnt_lo_u32_b32 v1, s6, 0
	v_mbcnt_hi_u32_b32 v1, s7, v1
	v_cmp_eq_u32_e32 vcc, 0, v1
	s_and_saveexec_b64 s[8:9], vcc
	s_cbranch_execz .LBB0_1067
	s_bcnt1_i32_b64 s6, s[6:7]
	v_mov_b32_e32 v2, 0x3000
	v_mov_b32_e32 v3, s6
	global_atomic_add v2, v2, v3, s[52:53] offset:1024 sc0

; __device__ __forceinline__ unsigned xb_ld(unsigned* p)              { return __hip_atomic_load(p, __ATOMIC_RELAXED, __HIP_MEMORY_SCOPE_AGENT); }
; __device__ __forceinline__ unsigned xb_add(unsigned* p, unsigned v) { return __hip_atomic_fetch_add(p, v, __ATOMIC_RELAXED, __HIP_MEMORY_SCOPE_AGENT); }
; #define XB_SPIN(cond, bar) do { unsigned _sp = 0; while (cond) { __builtin_amdgcn_s_sleep(1); \
;     if ((++_sp & 255u) == 0u) { if (xb_ld(&(bar)[XB_TMO])) break; if (_sp > XB_SPIN_CAP) { atomicAdd(&(bar)[XB_TMO], 1u); break; } } } } while (0)
; __device__ __forceinline__ void xcd_barrier(unsigned* bar, volatile LAS unsigned* st, bool tid0) {
;     ...
;             else XB_SPIN(xb_ld(&bar[XB_TOPGEN]) == tg, bar);
;             __builtin_amdgcn_fence(__ATOMIC_ACQUIRE, "agent");
;             xb_add(&bar[XB_XGEN(x)], 1u);
;             asm volatile("s_waitcnt vmcnt(0)" ::: "memory");
.LBB0_1081:
	s_or_b64 exec, exec, s[6:7]
	s_mov_b64 s[6:7], exec
	v_mbcnt_lo_u32_b32 v0, s6, 0
	v_mbcnt_hi_u32_b32 v0, s7, v0
	v_cmp_eq_u32_e32 vcc, 0, v0
	s_waitcnt vmcnt(0)
	s_and_saveexec_b64 s[8:9], vcc
	s_cbranch_execz .LBB0_1083
	s_bcnt1_i32_b64 s6, s[6:7]
	v_mov_b32_e32 v0, 0x2000
	v_mov_b32_e32 v1, s6
	global_atomic_add v0, v1, s[2:3] offset:1024
